# per-layer weight conversion split: only FFN1 w13 before the sync; remaining jobs done by workgroups >=128 (one GEMM tile fewer) ahead of their FFN1-up tiles
# speedup vs baseline: 1.0098x; 1.0006x over previous
; #define EWA_REP for (int rep_ = 0; rep_ < 2; ++rep_)
; __global__ void __launch_bounds__(512, 2) mega_fwd(KArgs a) {
;     ...
;     for (int l = 0; l < NL; ++l) {
;         const int j = l >> 1; const bool even = (l & 1) == 0;
;         if (l > 0) { { PH_VARS EWA_REP { CONV_LAYER(l); } } GSYNC(); }
.LBB0_1763:
	v_writelane_b32 v254, 0, 40
	s_add_i32 s1, s1, 1
	s_cmp_eq_u32 s1, 4
	s_cbranch_scc0 .LBB0_1764
	s_getpc_b64 s[98:99]

; #define LAS __attribute__((address_space(3)))
; __device__ __forceinline__ void conv_item(const float* __restrict__ W, const float* __restrict__ g, int K, int NS, int NP, bf16_t* __restrict__ dst, int ldd, int koff, int row_off, int ilv,
;                                           LAS float* scr, int item, int lane) {
;     ...
;     for (int j = 0; j < 16; ++j) {
;         const int idx = j * 64 + lane, nl = idx >> 3, q = idx & 7, nn = n0 + nl;
;         const u32x4 o = *(const LAS u32x4*)(tile + nl * 128 + ((q ^ ((nl >> 1) & 7)) << 4));
.LBB0_1764:
	s_lshr_b32 s0, s1, 1
	v_writelane_b32 v252, s0, 25
	s_and_b32 s0, s1, 1
	s_cmp_eq_u32 s0, 0
	s_cselect_b64 s[12:13], -1, 0
	s_cmp_eq_u32 s0, 1
	s_cselect_b64 s[2:3], -1, 0
	s_cmp_eq_u32 s1, 0
	s_cselect_b64 s[6:7], -1, 0
	v_writelane_b32 v252, s1, 26
	s_and_b64 vcc, exec, s[6:7]
	s_cbranch_vccnz .LBB0_3143
	s_mov_b64 s[0:1], s[88:89]
	v_mov_b32_e32 v1, v220
	s_movk_i32 s11, 0x70
	v_and_b32_e32 v4, 63, v1
	v_readfirstlane_b32 s4, v1
	s_waitcnt vmcnt(9)
	v_and_b32_e32 v70, 7, v1
	v_lshlrev_b32_e32 v5, 4, v4
	v_lshlrev_b32_e32 v2, 3, v1
	v_bfe_u32 v72, v1, 3, 3
	v_or_b32_e32 v1, 64, v4
	v_lshrrev_b32_e32 v75, 3, v1
	v_bitop3_b32 v77, v1, s11, v5 bitop3:0x48
	v_or_b32_e32 v1, 0xc0, v4
	v_lshrrev_b32_e32 v80, 3, v1
	v_bitop3_b32 v82, v1, s11, v5 bitop3:0x48
	v_or_b32_e32 v1, 0x140, v4
	v_lshrrev_b32_e32 v85, 3, v1
	v_bitop3_b32 v87, v1, s11, v5 bitop3:0x48
	v_or_b32_e32 v1, 0x1c0, v4
	s_waitcnt vmcnt(8)
	v_lshrrev_b32_e32 v90, 3, v1
	v_bitop3_b32 v92, v1, s11, v5 bitop3:0x48
	v_or_b32_e32 v1, 0x240, v4
	v_lshrrev_b32_e32 v95, 3, v1
	v_bitop3_b32 v97, v1, s11, v5 bitop3:0x48
	v_or_b32_e32 v1, 0x2c0, v4
	s_ashr_i32 s4, s4, 6
	v_readlane_b32 s5, v252, 0
	v_lshrrev_b32_e32 v100, 3, v1
	v_bitop3_b32 v102, v1, s11, v5 bitop3:0x48
	v_or_b32_e32 v1, 0x340, v4
	s_add_i32 s48, s4, s5
	s_lshl_b32 s4, s4, 14
	v_lshrrev_b32_e32 v105, 3, v1
	v_bitop3_b32 v107, v1, s11, v5 bitop3:0x48
	v_or_b32_e32 v1, 0x3c0, v4
	v_readlane_b32 s26, v252, 25
	s_add_i32 s10, s4, 0
	v_readlane_b32 s14, v252, 26
	v_or_b32_e32 v78, 16, v72
	v_or_b32_e32 v83, 32, v72
	v_or_b32_e32 v88, 48, v72
	v_or_b32_e32 v93, 64, v72
	v_or_b32_e32 v98, 0x50, v72
	v_or_b32_e32 v103, 0x60, v72
	v_or_b32_e32 v108, 0x70, v72
	v_lshrrev_b32_e32 v110, 3, v1
	s_mul_i32 s16, s26, 0x1b2000
	s_mov_b32 s17, s68
	s_lshl_b32 s18, s26, 20
	s_mov_b32 s19, s68
	s_mul_i32 s20, s26, 0x2a8000
	s_mov_b32 s21, s68
	s_mul_i32 s22, s26, 0x30000
	s_mov_b32 s23, s68
	s_lshl_b32 s24, s26, 17
	s_mov_b32 s25, s68
	s_mul_i32 s26, s26, 0xc0000
	s_mov_b32 s27, s68
	s_mul_i32 s4, s14, 0x580000
	s_mov_b32 s5, s68
	s_lshl_b32 s8, s14, 10
	s_mov_b32 s9, s68
	s_waitcnt lgkmcnt(0)
	v_lshlrev_b32_e32 v3, 1, v4
	v_lshl_add_u32 v71, v4, 8, s10
	v_and_b32_e32 v2, 56, v2
	v_bitop3_b32 v73, v5, s11, v4 bitop3:0x48
	v_lshl_add_u32 v74, v72, 7, s10
	v_lshl_add_u32 v76, v75, 7, s10
	v_lshl_add_u32 v79, v78, 7, s10
	v_lshl_add_u32 v81, v80, 7, s10
	v_lshl_add_u32 v84, v83, 7, s10
	v_lshl_add_u32 v86, v85, 7, s10
	v_lshl_add_u32 v89, v88, 7, s10
	v_lshl_add_u32 v91, v90, 7, s10
	v_lshl_add_u32 v94, v93, 7, s10
	v_lshl_add_u32 v96, v95, 7, s10
	v_lshl_add_u32 v99, v98, 7, s10
	v_lshl_add_u32 v101, v100, 7, s10
	v_lshl_add_u32 v104, v103, 7, s10
	v_lshl_add_u32 v106, v105, 7, s10
	v_lshl_add_u32 v109, v108, 7, s10
	v_lshl_add_u32 v111, v110, 7, s10
	v_bitop3_b32 v112, v1, s11, v5 bitop3:0x48
	s_mul_i32 s10, s14, 0x2c0000
	s_mov_b32 s11, s68
	s_lshl_b32 s14, s14, 20
	s_mov_b32 s15, s68
	s_lshl_b64 s[16:17], s[16:17], 2
	s_lshl_b64 s[18:19], s[18:19], 2
	s_lshl_b64 s[20:21], s[20:21], 2
	s_lshl_b64 s[22:23], s[22:23], 2
	s_lshl_b64 s[24:25], s[24:25], 2
	s_lshl_b64 s[26:27], s[26:27], 2
	v_readlane_b32 s28, v254, 40
	s_nop 1
	s_cmp_eq_u32 s28, 0
	s_cbranch_scc1 .Lmy_conv_m0
	s_addk_i32 s48, 0xfec0
.Lmy_conv_m0:
	s_branch .LBB0_1767
.LBB0_1766:
	v_readlane_b32 s49, v254, 40
	s_nop 1
	s_cmp_eq_u32 s49, 0
	s_cbranch_scc1 .Lmy_conv_inc0
	s_addk_i32 s48, 0xfc00

.LBB0_1872:
	v_readlane_b32 s30, v254, 40
	s_nop 1
	s_cmp_eq_u32 s30, 0
	s_cbranch_scc1 .LBB0_3090
	s_cmpk_gt_i32 s49, 0x15f
	s_cselect_b64 s[28:29], -1, 0
	s_mov_b64 s[30:31], -1
	s_and_b64 vcc, exec, s[28:29]
	s_cbranch_vccz .LBB0_1875
	s_mov_b32 s36, 53
	s_and_b64 vcc, exec, s[30:31]
	s_cbranch_vccnz .LBB0_1974

; __device__ __forceinline__ unsigned xb_ld(unsigned* p)              { return __hip_atomic_load(p, __ATOMIC_RELAXED, __HIP_MEMORY_SCOPE_AGENT); }
; __device__ __forceinline__ void xcd_barrier_complete(unsigned* bar, unsigned x, unsigned& nloc, unsigned& nx) {
;     const unsigned G = gridDim.x * gridDim.y * gridDim.z;
;     unsigned sum, cnt, mine, sp = 0u;
;     for (;;) {
;         sum = 0u; cnt = 0u; mine = 0u;
; #pragma unroll
;         for (unsigned j = 0; j < 16; ++j) { const unsigned c = xb_ld(&bar[XB_XCNT(j)]); sum += c; cnt += (c > 0u) ? 1u : 0u; mine = (j == x) ? c : mine; }
; __device__ __forceinline__ void xcd_barrier(const XcdBarrier& b) {
;     asm volatile("s_waitcnt vmcnt(0)" ::: "memory");
;     __syncthreads();
;     if (b.tid == 0u) {
;         unsigned* bar = b.bar;
;         __builtin_amdgcn_s_waitcnt(0);
;         unsigned nloc = b.st[0], nx = b.st[1];
;         if (nloc == 0u) { xcd_barrier_complete(bar, b.x, nloc, nx); b.st[0] = nloc; b.st[1] = nx; }
.LBB0_3090:
	v_readlane_b32 s4, v254, 40
	s_nop 1
	s_cmp_eq_u32 s4, 1
	s_cbranch_scc1 .Lmy_conv2_done
	s_mov_b64 s[4:5], s[88:89]
	s_getreg_b32 s8, hwreg(HW_REG_XCC_ID, 0, 4)
	s_waitcnt vmcnt(0)
	s_waitcnt lgkmcnt(0)
	s_barrier
	s_mov_b64 s[0:1], exec
	v_readlane_b32 s10, v252, 2
	v_readlane_b32 s11, v252, 3
	s_and_b64 s[10:11], s[0:1], s[10:11]
	s_mov_b64 exec, s[10:11]
	s_cbranch_execz .LBB0_3142
	v_readlane_b32 s9, v252, 13
	s_load_dwordx2 s[4:5], s[4:5], 0x100
	s_waitcnt vmcnt(0) expcnt(0) lgkmcnt(0)
	v_mov_b32_e32 v1, s9
	ds_read_b32 v3, v1
	v_readlane_b32 s9, v252, 14
	s_and_b32 s52, s8, 15
	s_waitcnt lgkmcnt(0)
	v_cmp_ne_u32_e32 vcc, 0, v3
	v_mov_b32_e32 v1, s9
	ds_read_b32 v2, v1
	s_cbranch_vccnz .LBB0_3106
	s_add_u32 s8, s4, 0x17900200
	s_addc_u32 s9, s5, 0
	s_add_u32 s10, s4, 0x17900400
	s_addc_u32 s11, s5, 0
	s_add_u32 s14, s4, 0x17900500
	s_addc_u32 s15, s5, 0
	s_add_u32 s16, s4, 0x17900600
	s_addc_u32 s17, s5, 0
	s_add_u32 s18, s4, 0x17900700
	s_addc_u32 s19, s5, 0
	s_add_u32 s20, s4, 0x17900800
	s_addc_u32 s21, s5, 0
	s_add_u32 s22, s4, 0x17900900
	s_addc_u32 s23, s5, 0
	s_add_u32 s24, s4, 0x17900a00
	s_addc_u32 s25, s5, 0
	s_add_u32 s26, s4, 0x17900b00
	s_addc_u32 s27, s5, 0
	s_add_u32 s28, s4, 0x17900c00
	s_addc_u32 s29, s5, 0
	s_add_u32 s30, s4, 0x17900d00
	s_addc_u32 s31, s5, 0
	s_add_u32 s34, s4, 0x17900e00
	s_addc_u32 s35, s5, 0
	s_add_u32 s36, s4, 0x17900f00
	s_addc_u32 s37, s5, 0
	s_add_u32 s38, s4, 0x17901000
	s_addc_u32 s39, s5, 0
	s_add_u32 s40, s4, 0x17901100
	s_addc_u32 s41, s5, 0
	s_add_u32 s42, s4, 0x17901200
	s_addc_u32 s43, s5, 0
	s_add_u32 s44, s4, 0x17901300
	s_addc_u32 s45, s5, 0
	s_mov_b32 s53, 1
	s_branch .LBB0_3094

; #define EWA_REP for (int rep_ = 0; rep_ < 2; ++rep_)
; __device__ __forceinline__ void xcd_barrier(const XcdBarrier& b) {
;     ...
;     __syncthreads();
; __global__ void __launch_bounds__(512, 2) mega_fwd(KArgs a) {
;     ...
;         if (l > 0) { { PH_VARS EWA_REP { CONV_LAYER(l); } } GSYNC(); }
.LBB0_3142:
	s_or_b64 exec, exec, s[0:1]
	s_waitcnt lgkmcnt(0)
	s_barrier
	s_cmpk_lt_u32 s86, 0x80
	s_cbranch_scc1 .LBB0_3143
	v_writelane_b32 v254, 1, 40
	v_readlane_b32 s1, v252, 26
	s_nop 1
	s_branch .LBB0_1764
.Lmy_conv2_done:
	s_waitcnt lgkmcnt(0)
	s_barrier
